# attention: row-sum v_add chain split into two independent interleaved accumulators (f32, +1 add)
# baseline (speedup 1.0000x reference)
; #define SBAR() __builtin_amdgcn_sched_barrier(0)
; #define SLOAD_B(k0) do { vs0b = *reinterpret_cast<const bf16x8*>(&Vh[(long)((k0) + sr) * LDK + sc]); vs1b = *reinterpret_cast<const bf16x8*>(&Vh[(long)((k0) + 32 + sr) * LDK + sc]); KLOAD(ks0b, ks1b, k0); } while (0)
; __device__ __forceinline__ void finishSM(f32x16& p0, f32x16& p1, float alpha, float& l_reg, bf16x8& pa0, bf16x8& pa1, bf16x8& pa2, bf16x8& pa3) {
; #pragma unroll
;   for (int r = 0; r < 16; ++r) p1[r] = __builtin_amdgcn_exp2f(p1[r]);
;   float ps = 0;
; #pragma unroll
;   for (int r = 0; r < 16; ++r) ps += p0[r];
; #pragma unroll
;   for (int r = 0; r < 16; ++r) ps += p1[r];
;   { auto rr = __builtin_amdgcn_permlane32_swap(__float_as_uint(ps), __float_as_uint(ps), false, false);
;     ps = __uint_as_float(rr[0]) + __uint_as_float(rr[1]); }
;   l_reg = l_reg * alpha + ps;
; template <int ND0, int LDQ, int LDK, int LDO> ...
;     ...
;     SBAR(); qkt<ND0>(pB0, pB1, Kq1, qr, r32, hi);
;     finishSM(pA0, pA1, alA, l_reg, pa0, pa1, pa2, pa3); SBAR();
;     SLOAD_B((j + 2) * KVBLK); SBAR();
.LBB0_146:
	ds_read_b128 v[208:211], v200 offset:49152
	ds_read_b128 v[214:217], v200 offset:57344
	v_exp_f32_e32 v170, v64
	v_add_f32_e32 v64, 0, v176
	s_waitcnt lgkmcnt(3)
	v_mfma_f32_32x32x16_bf16 v[96:111], v[80:83], v[114:117], 0
	v_add_f32_e32 v180, 0, v213
	v_add_f32_e32 v64, v174, v64
	v_add_f32_e32 v180, v177, v180
	v_add_f32_e32 v64, v173, v64
	v_add_f32_e32 v180, v175, v180
	v_add_f32_e32 v64, v171, v64
	v_add_f32_e32 v180, v172, v180
	s_waitcnt lgkmcnt(2)
	v_mfma_f32_32x32x16_bf16 v[80:95], v[84:87], v[114:117], 0
	v_add_f32_e32 v64, v167, v64
	v_add_f32_e32 v180, v169, v180
	v_add_f32_e32 v64, v166, v64
	v_add_f32_e32 v180, v168, v180
	v_add_f32_e32 v64, v163, v64
	v_add_f32_e32 v180, v165, v180
	v_add_f32_e32 v64, v162, v64
	s_waitcnt lgkmcnt(1)
	v_mfma_f32_32x32x16_bf16 v[96:111], v[208:211], v[122:125], v[96:111]
	v_exp_f32_e32 v212, v67
	v_add_f32_e32 v180, v164, v180
	v_add_f32_e32 v64, v170, v64
	v_exp_f32_e32 v218, v72
	v_exp_f32_e32 v219, v73
	v_exp_f32_e32 v220, v74
	v_exp_f32_e32 v221, v75
	s_waitcnt lgkmcnt(0)
	v_mfma_f32_32x32x16_bf16 v[80:95], v[214:217], v[122:125], v[80:95]
	ds_read_b128 v[208:211], v202 offset:49152
	ds_read_b128 v[214:217], v202 offset:57344
	v_exp_f32_e32 v222, v76
	v_exp_f32_e32 v223, v77
	v_exp_f32_e32 v224, v78
	v_exp_f32_e32 v79, v79
	s_waitcnt lgkmcnt(1)
	v_mfma_f32_32x32x16_bf16 v[96:111], v[208:211], v[142:145], v[96:111]
	s_waitcnt lgkmcnt(0)
	v_mfma_f32_32x32x16_bf16 v[80:95], v[214:217], v[142:145], v[80:95]
	ds_read_b128 v[208:211], v201 offset:49152
	ds_read_b128 v[214:217], v201 offset:57344
	s_waitcnt lgkmcnt(1)
	v_mfma_f32_32x32x16_bf16 v[96:111], v[208:211], v[138:141], v[96:111]
	s_waitcnt lgkmcnt(0)
	v_mfma_f32_32x32x16_bf16 v[80:95], v[214:217], v[138:141], v[80:95]
	ds_read_b128 v[208:211], v203 offset:49152
	ds_read_b128 v[214:217], v203 offset:57344
	s_waitcnt lgkmcnt(1)
	v_mfma_f32_32x32x16_bf16 v[96:111], v[208:211], v[134:137], v[96:111]
	s_waitcnt lgkmcnt(0)
	v_mfma_f32_32x32x16_bf16 v[80:95], v[214:217], v[134:137], v[80:95]
	ds_read_b128 v[208:211], v204 offset:49152
	ds_read_b128 v[214:217], v204 offset:57344
	s_waitcnt lgkmcnt(1)
	v_mfma_f32_32x32x16_bf16 v[96:111], v[208:211], v[130:133], v[96:111]
	s_waitcnt lgkmcnt(0)
	v_mfma_f32_32x32x16_bf16 v[80:95], v[214:217], v[130:133], v[80:95]
	ds_read_b128 v[208:211], v206 offset:49152
	ds_read_b128 v[214:217], v206 offset:57344
	s_waitcnt lgkmcnt(1)
	v_mfma_f32_32x32x16_bf16 v[96:111], v[208:211], v[126:129], v[96:111]
	s_waitcnt lgkmcnt(0)
	v_mfma_f32_32x32x16_bf16 v[80:95], v[214:217], v[126:129], v[80:95]
	ds_read_b128 v[208:211], v205 offset:49152
	ds_read_b128 v[214:217], v205 offset:57344
	s_waitcnt lgkmcnt(1)
	v_mfma_f32_32x32x16_bf16 v[96:111], v[208:211], v[118:121], v[96:111]
	v_exp_f32_e32 v210, v65
	v_exp_f32_e32 v211, v66
	v_add_f32_e32 v180, v210, v180
	v_add_f32_e32 v64, v211, v64
	v_add_f32_e32 v180, v212, v180
	s_waitcnt lgkmcnt(0)
	v_mfma_f32_32x32x16_bf16 v[80:95], v[214:217], v[118:121], v[80:95]
	v_exp_f32_e32 v214, v68
	v_exp_f32_e32 v215, v69
	v_exp_f32_e32 v216, v70
	v_exp_f32_e32 v217, v71
	v_add_f32_e32 v64, v214, v64
	v_add_f32_e32 v180, v215, v180
	v_add_f32_e32 v64, v216, v64
	v_add_f32_e32 v180, v217, v180
	v_add_f32_e32 v64, v218, v64
	v_add_f32_e32 v180, v219, v180
	v_add_f32_e32 v64, v220, v64
	v_add_f32_e32 v180, v221, v180
	v_add_f32_e32 v64, v222, v64
	v_add_f32_e32 v180, v223, v180
	v_add_f32_e32 v64, v224, v64
	v_add_f32_e32 v180, v79, v180
	v_add_f32_e32 v208, v180, v64
	v_mov_b32_e32 v209, v208
	s_nop 1
	v_permlane32_swap_b32_e32 v208, v209
	v_cvt_pk_bf16_f32 v64, v176, v213
	v_cvt_pk_bf16_f32 v65, v174, v177
	v_cvt_pk_bf16_f32 v66, v173, v175
	v_cvt_pk_bf16_f32 v67, v171, v172
	v_cvt_pk_bf16_f32 v68, v167, v169
	v_cvt_pk_bf16_f32 v69, v166, v168
	v_cvt_pk_bf16_f32 v70, v163, v165
	v_cvt_pk_bf16_f32 v71, v162, v164
	v_cvt_pk_bf16_f32 v72, v170, v210
	v_cvt_pk_bf16_f32 v73, v211, v212
	v_cvt_pk_bf16_f32 v74, v214, v215
	v_cvt_pk_bf16_f32 v75, v216, v217
	v_cvt_pk_bf16_f32 v76, v218, v219
	v_cvt_pk_bf16_f32 v77, v220, v221
	v_cvt_pk_bf16_f32 v78, v222, v223
	v_cvt_pk_bf16_f32 v79, v224, v79
	s_nop 0
	v_permlane32_swap_b32_e32 v64, v66
	v_permlane32_swap_b32_e32 v65, v67
	v_permlane32_swap_b32_e32 v68, v70
	v_permlane32_swap_b32_e32 v69, v71
	v_permlane32_swap_b32_e32 v72, v74
	v_permlane32_swap_b32_e32 v73, v75
	v_permlane32_swap_b32_e32 v76, v78
	v_permlane32_swap_b32_e32 v77, v79
	s_mov_b32 s4, 0xfffb8000
	v_add_co_u32_e32 v166, vcc, s4, v188
	s_mov_b32 s4, 0xfffd0000
	s_nop 0
	v_addc_co_u32_e32 v167, vcc, -1, v189, vcc
	v_add_co_u32_e32 v174, vcc, s4, v188
	s_nop 1
	v_addc_co_u32_e32 v175, vcc, -1, v189, vcc
	global_load_dwordx4 v[162:165], v[166:167], off
	global_load_dwordx4 v[170:173], v[166:167], off offset:-512
	s_nop 0
	global_load_dwordx4 v[166:169], v[174:175], off
	s_nop 0
	global_load_dwordx4 v[174:177], v[174:175], off offset:-512
	v_cmp_neq_f32_e32 vcc, 0, v193
	ds_read_b64_tr_b16 v[210:211], v194 offset:0
	ds_read_b64_tr_b16 v[212:213], v194 offset:0x800
	ds_read_b64_tr_b16 v[214:215], v194 offset:0x1000
	ds_read_b64_tr_b16 v[216:217], v194 offset:0x1800
	ds_read_b64_tr_b16 v[218:219], v194 offset:0x2000
	ds_read_b64_tr_b16 v[220:221], v194 offset:0x2800
	ds_read_b64_tr_b16 v[222:223], v194 offset:0x3000
	ds_read_b64_tr_b16 v[224:225], v194 offset:0x3800
	s_cbranch_vccnz .LBB0_163

; #define SBAR() __builtin_amdgcn_sched_barrier(0)
; #define SLOAD_A(k0) do { vs0a = *reinterpret_cast<const bf16x8*>(&Vh[(long)((k0) + sr) * LDK + sc]); vs1a = *reinterpret_cast<const bf16x8*>(&Vh[(long)((k0) + 32 + sr) * LDK + sc]); KLOAD(ks0a, ks1a, k0); } while (0)
; __device__ __forceinline__ void finishSM(f32x16& p0, f32x16& p1, float alpha, float& l_reg, bf16x8& pa0, bf16x8& pa1, bf16x8& pa2, bf16x8& pa3) {
; #pragma unroll
;   for (int r = 0; r < 16; ++r) p1[r] = __builtin_amdgcn_exp2f(p1[r]);
;   float ps = 0;
; #pragma unroll
;   for (int r = 0; r < 16; ++r) ps += p0[r];
; #pragma unroll
;   for (int r = 0; r < 16; ++r) ps += p1[r];
;   { auto rr = __builtin_amdgcn_permlane32_swap(__float_as_uint(ps), __float_as_uint(ps), false, false);
;     ps = __uint_as_float(rr[0]) + __uint_as_float(rr[1]); }
;   l_reg = l_reg * alpha + ps;
; template <int ND0, int LDQ, int LDK, int LDO> ...
;     ...
;     SBAR(); qkt<ND0>(pA0, pA1, Kq0, qr, r32, hi);
;     finishSM(pB0, pB1, alB, l_reg, pa0, pa1, pa2, pa3); SBAR();
;     if (j + 3 < NT) SLOAD_A((j + 3) * KVBLK); SBAR();
.LBB0_153:
	v_mov_b32_e32 v242, 0x800
	ds_read_b128 v[64:67], v199 offset:32768
	ds_read_b128 v[68:71], v199 offset:40960
	ds_read_b128 v[238:241], v200 offset:32768
	ds_read_b128 v[234:237], v200 offset:40960
	v_exp_f32_e32 v245, v88
	v_exp_f32_e32 v246, v89
	s_waitcnt lgkmcnt(3)
	v_mfma_f32_32x32x16_bf16 v[96:111], v[64:67], v[114:117], 0
	v_exp_f32_e32 v247, v90
	v_exp_f32_e32 v231, v91
	v_exp_f32_e32 v243, v92
	v_exp_f32_e32 v252, v93
	v_exp_f32_e32 v253, v94
	v_exp_f32_e32 v95, v95
	s_waitcnt lgkmcnt(2)
	v_mfma_f32_32x32x16_bf16 v[64:79], v[68:71], v[114:117], 0
	s_waitcnt lgkmcnt(1)
	v_mfma_f32_32x32x16_bf16 v[96:111], v[238:241], v[122:125], v[96:111]
	s_waitcnt lgkmcnt(0)
	v_mfma_f32_32x32x16_bf16 v[64:79], v[234:237], v[122:125], v[64:79]
	ds_read_b128 v[234:237], v202 offset:32768
	ds_read_b128 v[238:241], v202 offset:40960
	s_waitcnt lgkmcnt(1)
	v_mfma_f32_32x32x16_bf16 v[96:111], v[234:237], v[142:145], v[96:111]
	s_waitcnt lgkmcnt(0)
	v_mfma_f32_32x32x16_bf16 v[64:79], v[238:241], v[142:145], v[64:79]
	ds_read_b128 v[234:237], v201 offset:32768
	ds_read_b128 v[238:241], v201 offset:40960
	s_waitcnt lgkmcnt(1)
	v_mfma_f32_32x32x16_bf16 v[96:111], v[234:237], v[138:141], v[96:111]
	s_waitcnt lgkmcnt(0)
	v_mfma_f32_32x32x16_bf16 v[64:79], v[238:241], v[138:141], v[64:79]
	ds_read_b128 v[234:237], v203 offset:32768
	ds_read_b128 v[238:241], v203 offset:40960
	s_waitcnt lgkmcnt(1)
	v_mfma_f32_32x32x16_bf16 v[96:111], v[234:237], v[134:137], v[96:111]
	s_waitcnt lgkmcnt(0)
	v_mfma_f32_32x32x16_bf16 v[64:79], v[238:241], v[134:137], v[64:79]
	ds_read_b128 v[234:237], v204 offset:32768
	ds_read_b128 v[238:241], v204 offset:40960
	s_waitcnt lgkmcnt(1)
	v_mfma_f32_32x32x16_bf16 v[96:111], v[234:237], v[130:133], v[96:111]
	s_waitcnt lgkmcnt(0)
	v_mfma_f32_32x32x16_bf16 v[64:79], v[238:241], v[130:133], v[64:79]
	ds_read_b128 v[234:237], v206 offset:32768
	ds_read_b128 v[238:241], v206 offset:40960
	s_waitcnt lgkmcnt(1)
	v_mfma_f32_32x32x16_bf16 v[96:111], v[234:237], v[126:129], v[96:111]
	s_waitcnt lgkmcnt(0)
	v_mfma_f32_32x32x16_bf16 v[64:79], v[238:241], v[126:129], v[64:79]
	ds_read_b128 v[234:237], v205 offset:32768
	ds_read_b128 v[238:241], v205 offset:40960
	s_waitcnt lgkmcnt(1)
	v_mfma_f32_32x32x16_bf16 v[96:111], v[234:237], v[118:121], v[96:111]
	v_exp_f32_e32 v234, v80
	v_add_f32_e32 v80, 0, v226
	v_add_f32_e32 v180, 0, v244
	v_add_f32_e32 v80, v224, v80
	v_add_f32_e32 v180, v227, v180
	v_add_f32_e32 v80, v223, v80
	v_add_f32_e32 v180, v225, v180
	v_add_f32_e32 v80, v221, v80
	v_add_f32_e32 v180, v222, v180
	v_add_f32_e32 v80, v218, v80
	v_add_f32_e32 v180, v220, v180
	v_add_f32_e32 v80, v217, v80
	v_add_f32_e32 v180, v219, v180
	v_add_f32_e32 v80, v214, v80
	v_exp_f32_e32 v235, v81
	v_add_f32_e32 v180, v216, v180
	v_exp_f32_e32 v236, v82
	v_add_f32_e32 v80, v213, v80
	v_exp_f32_e32 v237, v83
	v_add_f32_e32 v180, v215, v180
	s_waitcnt lgkmcnt(0)
	v_mfma_f32_32x32x16_bf16 v[64:79], v[238:241], v[118:121], v[64:79]
	v_exp_f32_e32 v238, v84
	v_add_f32_e32 v80, v234, v80
	v_exp_f32_e32 v239, v85
	v_add_f32_e32 v180, v235, v180
	v_exp_f32_e32 v240, v86
	v_add_f32_e32 v80, v236, v80
	v_exp_f32_e32 v241, v87
	v_add_f32_e32 v180, v237, v180
	v_add_f32_e32 v80, v238, v80
	v_add_f32_e32 v180, v239, v180
	v_add_f32_e32 v80, v240, v80
	v_add_f32_e32 v180, v241, v180
	v_add_f32_e32 v80, v245, v80
	v_add_f32_e32 v180, v246, v180
	v_add_f32_e32 v80, v247, v80
	v_add_f32_e32 v180, v231, v180
	v_add_f32_e32 v80, v243, v80
	v_add_f32_e32 v180, v252, v180
	v_add_f32_e32 v80, v253, v80
	v_add_f32_e32 v180, v95, v180
	v_add_f32_e32 v211, v180, v80
	v_mov_b32_e32 v212, v211
	v_cvt_pk_bf16_f32 v80, v226, v244
	v_cvt_pk_bf16_f32 v81, v224, v227
	v_cvt_pk_bf16_f32 v82, v223, v225
	v_cvt_pk_bf16_f32 v83, v221, v222
	v_cvt_pk_bf16_f32 v84, v218, v220
	v_cvt_pk_bf16_f32 v85, v217, v219
	v_cvt_pk_bf16_f32 v86, v214, v216
	v_cvt_pk_bf16_f32 v87, v213, v215
	v_cvt_pk_bf16_f32 v88, v234, v235
	v_cvt_pk_bf16_f32 v89, v236, v237
	v_cvt_pk_bf16_f32 v90, v238, v239
	v_cvt_pk_bf16_f32 v91, v240, v241
	v_cvt_pk_bf16_f32 v92, v245, v246
	v_cvt_pk_bf16_f32 v93, v247, v231
	v_cvt_pk_bf16_f32 v94, v243, v252
	v_cvt_pk_bf16_f32 v95, v253, v95
	s_nop 1
	v_permlane32_swap_b32_e32 v211, v212
	v_permlane32_swap_b32_e32 v80, v82
	v_permlane32_swap_b32_e32 v81, v83
	v_permlane32_swap_b32_e32 v84, v86
	v_permlane32_swap_b32_e32 v85, v87
	v_permlane32_swap_b32_e32 v88, v90
	v_permlane32_swap_b32_e32 v89, v91
	v_permlane32_swap_b32_e32 v92, v94
	v_permlane32_swap_b32_e32 v93, v95
	s_add_i32 s39, s39, 2
	s_cmp_ge_u32 s39, s38
	s_cselect_b64 s[4:5], -1, 0
	s_and_b64 vcc, exec, s[4:5]
	s_cbranch_vccnz .Lgqa_pf_skip
	v_add_co_u32_e32 v146, vcc, 0xfffe8000, v188
	s_nop 1
	v_addc_co_u32_e32 v147, vcc, -1, v189, vcc
	global_load_dwordx4 v[158:161], v[146:147], off
	global_load_dwordx4 v[150:153], v[146:147], off offset:-512
	global_load_dwordx4 v[154:157], v[188:189], off
	s_nop 0
	global_load_dwordx4 v[146:149], v[188:189], off offset:-512

; #define SBAR() __builtin_amdgcn_sched_barrier(0)
; #define KWRITE(b, src0, src1) do { if constexpr (ND0 == 4) { *(bf16x8*)(K_lds + (b) * SHM_K + KSWZ(kr, kcb)) = src0; } \
;     else { int kc = sc * 2; *(bf16x8*)(K_lds + (b) * SHM_K + KSWZ(sr, kc)) = src0; *(bf16x8*)(K_lds + (b) * SHM_K + KSWZ(32 + sr, kc)) = src1; } } while (0)
; #define SLOAD_B(k0) do { vs0b = *reinterpret_cast<const bf16x8*>(&Vh[(long)((k0) + sr) * LDK + sc]); vs1b = *reinterpret_cast<const bf16x8*>(&Vh[(long)((k0) + 32 + sr) * LDK + sc]); KLOAD(ks0b, ks1b, k0); } while (0)
; #define PSM(P0, P1, MN, AL) do { if constexpr (PRE) partialSM_pre(P0, P1, m_reg, AL, 11.541560327111707f); else partialSM(P0, P1, m_reg, MN, AL, C, thr_raw); } while (0)
; __device__ __forceinline__ void finishSM(f32x16& p0, f32x16& p1, float alpha, float& l_reg, bf16x8& pa0, bf16x8& pa1, bf16x8& pa2, bf16x8& pa3) {
; #pragma unroll
;   for (int r = 0; r < 16; ++r) p1[r] = __builtin_amdgcn_exp2f(p1[r]);
;   float ps = 0;
; #pragma unroll
;   for (int r = 0; r < 16; ++r) ps += p0[r];
; #pragma unroll
;   for (int r = 0; r < 16; ++r) ps += p1[r];
;   { auto rr = __builtin_amdgcn_permlane32_swap(__float_as_uint(ps), __float_as_uint(ps), false, false);
;     ps = __uint_as_float(rr[0]) + __uint_as_float(rr[1]); }
;   l_reg = l_reg * alpha + ps;
;     ...
;   PK4(p0, 0, pa0); PK4(p0, 8, pa1); PK4(p1, 0, pa2); PK4(p1, 8, pa3);
;     ...
; }
; template <int ND0>
; __device__ __forceinline__ void qkt(f32x16& p0, f32x16& p1, const char* Ks, const bf16x8* qr, int r32, int hi) {
;   p0 = f32x16{}; p1 = f32x16{};
; #pragma unroll
;   for (int d0 = 0; d0 < ND0; ++d0) { int cb = (d0 * 16 + hi * 8) * 2;
;     bf16x8 b0 = *reinterpret_cast<const bf16x8*>(Ks + KSWZ(r32, cb));
;     bf16x8 b1 = *reinterpret_cast<const bf16x8*>(Ks + KSWZ(32 + r32, cb));
;     p0 = __builtin_amdgcn_mfma_f32_32x32x16_bf16(b0, qr[d0], p0, 0, 0, 0);
;     p1 = __builtin_amdgcn_mfma_f32_32x32x16_bf16(b1, qr[d0], p1, 0, 0, 0); }
; }
; template <int ND0, int LDQ, int LDK, int LDO> ...
;     ...
;   for (int j = 1; j + 1 < NT; j += 2) {
;     SBAR(); qkt<ND0>(pB0, pB1, Kq1, qr, r32, hi);
;     finishSM(pA0, pA1, alA, l_reg, pa0, pa1, pa2, pa3); SBAR();
;     SLOAD_B((j + 2) * KVBLK); SBAR();
;     pv_d0(o, vb0, pa0, pa1, pa2, pa3); KWRITE(0, ks0a, ks1a); PSM(pB0, pB1, mnB, alB);
.LBB0_214:
	ds_read_b128 v[202:205], v198 offset:49152
	ds_read_b128 v[208:211], v198 offset:57344
	v_exp_f32_e32 v150, v64
	v_add_f32_e32 v64, 0, v176
	s_waitcnt lgkmcnt(3)
	v_mfma_f32_32x32x16_bf16 v[96:111], v[80:83], v[126:129], 0
	v_add_f32_e32 v231, 0, v206
	v_add_f32_e32 v64, v174, v64
	v_add_f32_e32 v231, v177, v231
	v_add_f32_e32 v64, v152, v64
	v_add_f32_e32 v231, v175, v231
	v_add_f32_e32 v64, v151, v64
	v_add_f32_e32 v231, v153, v231
	s_waitcnt lgkmcnt(2)
	v_mfma_f32_32x32x16_bf16 v[80:95], v[84:87], v[126:129], 0
	v_add_f32_e32 v64, v147, v64
	v_add_f32_e32 v231, v149, v231
	v_add_f32_e32 v64, v145, v64
	v_add_f32_e32 v231, v148, v231
	v_add_f32_e32 v64, v143, v64
	v_add_f32_e32 v231, v146, v231
	v_add_f32_e32 v64, v142, v64
	s_waitcnt lgkmcnt(1)
	v_mfma_f32_32x32x16_bf16 v[96:111], v[202:205], v[122:125], v[96:111]
	v_add_f32_e32 v231, v144, v231
	v_exp_f32_e32 v207, v68
	v_add_f32_e32 v64, v150, v64
	v_exp_f32_e32 v212, v73
	v_exp_f32_e32 v213, v74
	v_exp_f32_e32 v214, v75
	v_exp_f32_e32 v215, v76
	s_waitcnt lgkmcnt(0)
	v_mfma_f32_32x32x16_bf16 v[80:95], v[208:211], v[122:125], v[80:95]
	ds_read_b128 v[202:205], v199 offset:49152
	ds_read_b128 v[208:211], v199 offset:57344
	v_exp_f32_e32 v216, v77
	v_exp_f32_e32 v217, v78
	v_exp_f32_e32 v79, v79
	s_waitcnt lgkmcnt(1)
	v_mfma_f32_32x32x16_bf16 v[96:111], v[202:205], v[118:121], v[96:111]
	s_waitcnt lgkmcnt(0)
	v_mfma_f32_32x32x16_bf16 v[80:95], v[208:211], v[118:121], v[80:95]
	ds_read_b128 v[202:205], v196 offset:49152
	ds_read_b128 v[208:211], v196 offset:57344
	s_waitcnt lgkmcnt(1)
	v_mfma_f32_32x32x16_bf16 v[96:111], v[202:205], v[114:117], v[96:111]
	v_exp_f32_e32 v203, v65
	v_exp_f32_e32 v204, v66
	v_exp_f32_e32 v205, v67
	v_add_f32_e32 v231, v203, v231
	v_add_f32_e32 v64, v204, v64
	v_add_f32_e32 v231, v205, v231
	s_waitcnt lgkmcnt(0)
	v_mfma_f32_32x32x16_bf16 v[80:95], v[208:211], v[114:117], v[80:95]
	v_exp_f32_e32 v208, v69
	v_exp_f32_e32 v209, v70
	v_exp_f32_e32 v210, v71
	v_exp_f32_e32 v211, v72
	v_add_f32_e32 v64, v207, v64
	v_add_f32_e32 v231, v208, v231
	v_add_f32_e32 v64, v209, v64
	v_add_f32_e32 v231, v210, v231
	v_add_f32_e32 v64, v211, v64
	v_add_f32_e32 v231, v212, v231
	v_add_f32_e32 v64, v213, v64
	v_add_f32_e32 v231, v214, v231
	v_add_f32_e32 v64, v215, v64
	v_add_f32_e32 v231, v216, v231
	v_add_f32_e32 v64, v217, v64
	v_add_f32_e32 v231, v79, v231
	v_add_f32_e32 v201, v231, v64
	v_mov_b32_e32 v202, v201
	s_nop 1
	v_permlane32_swap_b32_e32 v201, v202
	v_cvt_pk_bf16_f32 v64, v176, v206
	v_cvt_pk_bf16_f32 v65, v174, v177
	v_cvt_pk_bf16_f32 v66, v152, v175
	v_cvt_pk_bf16_f32 v67, v151, v153
	v_cvt_pk_bf16_f32 v68, v147, v149
	v_cvt_pk_bf16_f32 v69, v145, v148
	v_cvt_pk_bf16_f32 v70, v143, v146
	v_cvt_pk_bf16_f32 v71, v142, v144
	v_cvt_pk_bf16_f32 v72, v150, v203
	v_cvt_pk_bf16_f32 v73, v204, v205
	v_cvt_pk_bf16_f32 v74, v207, v208
	v_cvt_pk_bf16_f32 v75, v209, v210
	v_cvt_pk_bf16_f32 v76, v211, v212
	v_cvt_pk_bf16_f32 v77, v213, v214
	v_cvt_pk_bf16_f32 v78, v215, v216
	v_cvt_pk_bf16_f32 v79, v217, v79
	s_nop 0
	v_permlane32_swap_b32_e32 v64, v66
	v_permlane32_swap_b32_e32 v65, v67
	v_permlane32_swap_b32_e32 v68, v70
	v_permlane32_swap_b32_e32 v69, v71
	v_permlane32_swap_b32_e32 v72, v74
	v_permlane32_swap_b32_e32 v73, v75
	v_permlane32_swap_b32_e32 v76, v78
	v_permlane32_swap_b32_e32 v77, v79
	v_lshl_add_u64 v[174:175], v[172:173], 0, s[34:35]
	s_mov_b32 s18, 0x13221000
	v_add_co_u32_e32 v142, vcc, s18, v174
	s_mov_b32 s18, 0x13251000
	s_nop 0
	v_addc_co_u32_e32 v143, vcc, 0, v175, vcc
	v_add_co_u32_e32 v146, vcc, s18, v174
	v_lshl_add_u64 v[176:177], v[170:171], 0, s[34:35]
	s_nop 0
	v_addc_co_u32_e32 v147, vcc, 0, v175, vcc
	s_mov_b32 s18, 0x13220000
	v_add_co_u32_e32 v150, vcc, s18, v176
	global_load_dwordx4 v[142:145], v[142:143], off
	s_nop 0
	global_load_dwordx4 v[146:149], v[146:147], off
	v_addc_co_u32_e32 v151, vcc, 0, v177, vcc
	global_load_dwordx4 v[150:153], v[150:151], off offset:2048
	v_cmp_neq_f32_e32 vcc, 0, v191
	ds_read_b64_tr_b16 v[204:205], v192 offset:0
	ds_read_b64_tr_b16 v[206:207], v192 offset:0x800
	ds_read_b64_tr_b16 v[208:209], v192 offset:0x1000
	ds_read_b64_tr_b16 v[210:211], v192 offset:0x1800
	ds_read_b64_tr_b16 v[212:213], v192 offset:0x2000
	ds_read_b64_tr_b16 v[214:215], v192 offset:0x2800
	ds_read_b64_tr_b16 v[216:217], v192 offset:0x3000
	ds_read_b64_tr_b16 v[218:219], v192 offset:0x3800
	s_cbranch_vccnz .LBB0_230

; #define SBAR() __builtin_amdgcn_sched_barrier(0)
; #define KWRITE(b, src0, src1) do { if constexpr (ND0 == 4) { *(bf16x8*)(K_lds + (b) * SHM_K + KSWZ(kr, kcb)) = src0; } \
;     else { int kc = sc * 2; *(bf16x8*)(K_lds + (b) * SHM_K + KSWZ(sr, kc)) = src0; *(bf16x8*)(K_lds + (b) * SHM_K + KSWZ(32 + sr, kc)) = src1; } } while (0)
; #define SLOAD_A(k0) do { vs0a = *reinterpret_cast<const bf16x8*>(&Vh[(long)((k0) + sr) * LDK + sc]); vs1a = *reinterpret_cast<const bf16x8*>(&Vh[(long)((k0) + 32 + sr) * LDK + sc]); KLOAD(ks0a, ks1a, k0); } while (0)
; #define PSM(P0, P1, MN, AL) do { if constexpr (PRE) partialSM_pre(P0, P1, m_reg, AL, 11.541560327111707f); else partialSM(P0, P1, m_reg, MN, AL, C, thr_raw); } while (0)
; __device__ __forceinline__ void finishSM(f32x16& p0, f32x16& p1, float alpha, float& l_reg, bf16x8& pa0, bf16x8& pa1, bf16x8& pa2, bf16x8& pa3) {
; #pragma unroll
;   for (int r = 0; r < 16; ++r) p1[r] = __builtin_amdgcn_exp2f(p1[r]);
;   float ps = 0;
; #pragma unroll
;   for (int r = 0; r < 16; ++r) ps += p0[r];
; #pragma unroll
;   for (int r = 0; r < 16; ++r) ps += p1[r];
;   { auto rr = __builtin_amdgcn_permlane32_swap(__float_as_uint(ps), __float_as_uint(ps), false, false);
;     ps = __uint_as_float(rr[0]) + __uint_as_float(rr[1]); }
;   l_reg = l_reg * alpha + ps;
;     ...
;   PK4(p0, 0, pa0); PK4(p0, 8, pa1); PK4(p1, 0, pa2); PK4(p1, 8, pa3);
;     ...
; }
; template <int ND0>
; __device__ __forceinline__ void qkt(f32x16& p0, f32x16& p1, const char* Ks, const bf16x8* qr, int r32, int hi) {
;   p0 = f32x16{}; p1 = f32x16{};
; #pragma unroll
;   for (int d0 = 0; d0 < ND0; ++d0) { int cb = (d0 * 16 + hi * 8) * 2;
;     bf16x8 b0 = *reinterpret_cast<const bf16x8*>(Ks + KSWZ(r32, cb));
;     bf16x8 b1 = *reinterpret_cast<const bf16x8*>(Ks + KSWZ(32 + r32, cb));
;     p0 = __builtin_amdgcn_mfma_f32_32x32x16_bf16(b0, qr[d0], p0, 0, 0, 0);
;     p1 = __builtin_amdgcn_mfma_f32_32x32x16_bf16(b1, qr[d0], p1, 0, 0, 0); }
; }
; template <int ND0, int LDQ, int LDK, int LDO> ...
;     ...
;     SBAR(); qkt<ND0>(pA0, pA1, Kq0, qr, r32, hi);
;     finishSM(pB0, pB1, alB, l_reg, pa0, pa1, pa2, pa3); SBAR();
;     if (j + 3 < NT) SLOAD_A((j + 3) * KVBLK); SBAR();
;     pv_d0(o, vb0 + (int)SHM_V, pa0, pa1, pa2, pa3); KWRITE(1, ks0b, ks1b); PSM(pA0, pA1, mnA, alA);
.LBB0_220:
	ds_read_b128 v[64:67], v197 offset:32768
	ds_read_b128 v[68:71], v197 offset:40960
	ds_read_b128 v[222:225], v198 offset:32768
	ds_read_b128 v[244:247], v198 offset:40960
	v_exp_f32_e32 v226, v84
	v_exp_f32_e32 v227, v85
	s_waitcnt lgkmcnt(3)
	v_mfma_f32_32x32x16_bf16 v[96:111], v[64:67], v[126:129], 0
	v_exp_f32_e32 v234, v86
	v_exp_f32_e32 v235, v87
	v_exp_f32_e32 v236, v88
	v_exp_f32_e32 v237, v89
	v_exp_f32_e32 v238, v90
	v_exp_f32_e32 v239, v91
	v_exp_f32_e32 v240, v92
	s_waitcnt lgkmcnt(2)
	v_mfma_f32_32x32x16_bf16 v[64:79], v[68:71], v[126:129], 0
	v_exp_f32_e32 v241, v93
	v_exp_f32_e32 v95, v95
	s_waitcnt lgkmcnt(1)
	v_mfma_f32_32x32x16_bf16 v[96:111], v[222:225], v[122:125], v[96:111]
	s_waitcnt lgkmcnt(0)
	v_mfma_f32_32x32x16_bf16 v[64:79], v[244:247], v[122:125], v[64:79]
	ds_read_b128 v[222:225], v199 offset:32768
	ds_read_b128 v[244:247], v199 offset:40960
	s_waitcnt lgkmcnt(1)
	v_mfma_f32_32x32x16_bf16 v[96:111], v[222:225], v[118:121], v[96:111]
	s_waitcnt lgkmcnt(0)
	v_mfma_f32_32x32x16_bf16 v[64:79], v[244:247], v[118:121], v[64:79]
	ds_read_b128 v[222:225], v196 offset:32768
	ds_read_b128 v[244:247], v196 offset:40960
	s_waitcnt lgkmcnt(1)
	v_mfma_f32_32x32x16_bf16 v[96:111], v[222:225], v[114:117], v[96:111]
	v_exp_f32_e32 v222, v80
	v_add_f32_e32 v80, 0, v219
	v_add_f32_e32 v231, 0, v221
	v_add_f32_e32 v80, v217, v80
	v_add_f32_e32 v231, v220, v231
	v_add_f32_e32 v80, v215, v80
	v_add_f32_e32 v231, v218, v231
	v_add_f32_e32 v80, v214, v80
	v_add_f32_e32 v231, v216, v231
	v_add_f32_e32 v80, v211, v80
	v_add_f32_e32 v231, v213, v231
	v_add_f32_e32 v80, v209, v80
	v_add_f32_e32 v231, v212, v231
	v_add_f32_e32 v80, v207, v80
	v_exp_f32_e32 v223, v81
	v_add_f32_e32 v231, v210, v231
	v_exp_f32_e32 v224, v82
	v_add_f32_e32 v80, v206, v80
	v_exp_f32_e32 v225, v83
	v_add_f32_e32 v231, v208, v231
	v_add_f32_e32 v80, v222, v80
	v_add_f32_e32 v231, v223, v231
	v_add_f32_e32 v80, v224, v80
	v_add_f32_e32 v231, v225, v231
	v_add_f32_e32 v80, v226, v80
	v_add_f32_e32 v231, v227, v231
	v_add_f32_e32 v80, v234, v80
	v_add_f32_e32 v231, v235, v231
	v_add_f32_e32 v80, v236, v80
	v_add_f32_e32 v231, v237, v231
	s_waitcnt lgkmcnt(0)
	v_mfma_f32_32x32x16_bf16 v[64:79], v[244:247], v[114:117], v[64:79]
	v_exp_f32_e32 v244, v94
	v_add_f32_e32 v80, v238, v80
	v_add_f32_e32 v231, v239, v231
	v_add_f32_e32 v80, v240, v80
	v_add_f32_e32 v231, v241, v231
	v_add_f32_e32 v80, v244, v80
	v_add_f32_e32 v231, v95, v231
	v_add_f32_e32 v204, v231, v80
	v_mov_b32_e32 v205, v204
	v_cvt_pk_bf16_f32 v80, v219, v221
	v_cvt_pk_bf16_f32 v81, v217, v220
	v_cvt_pk_bf16_f32 v82, v215, v218
	v_cvt_pk_bf16_f32 v83, v214, v216
	v_cvt_pk_bf16_f32 v84, v211, v213
	v_cvt_pk_bf16_f32 v85, v209, v212
	v_cvt_pk_bf16_f32 v86, v207, v210
	v_cvt_pk_bf16_f32 v87, v206, v208
	v_cvt_pk_bf16_f32 v88, v222, v223
	v_cvt_pk_bf16_f32 v89, v224, v225
	v_cvt_pk_bf16_f32 v90, v226, v227
	v_cvt_pk_bf16_f32 v91, v234, v235
	v_cvt_pk_bf16_f32 v92, v236, v237
	v_cvt_pk_bf16_f32 v93, v238, v239
	v_cvt_pk_bf16_f32 v94, v240, v241
	v_cvt_pk_bf16_f32 v95, v244, v95
	s_nop 1
	v_permlane32_swap_b32_e32 v204, v205
	v_permlane32_swap_b32_e32 v80, v82
	v_permlane32_swap_b32_e32 v81, v83
	v_permlane32_swap_b32_e32 v84, v86
	v_permlane32_swap_b32_e32 v85, v87
	v_permlane32_swap_b32_e32 v88, v90
	v_permlane32_swap_b32_e32 v89, v91
	v_permlane32_swap_b32_e32 v92, v94
	v_permlane32_swap_b32_e32 v93, v95
	s_cmp_ge_u32 s40, s39
	s_cselect_b64 s[18:19], -1, 0
	s_and_b64 vcc, exec, s[18:19]
	s_cbranch_vccnz .Ldiff_pf_skip
	v_add_co_u32_e32 v130, vcc, 0x13281000, v174
	s_nop 1
	v_addc_co_u32_e32 v131, vcc, 0, v175, vcc
	v_add_co_u32_e32 v134, vcc, 0x132b1000, v174
	s_nop 1
	v_addc_co_u32_e32 v135, vcc, 0, v175, vcc
	v_add_co_u32_e32 v138, vcc, 0x13280000, v176
	global_load_dwordx4 v[130:133], v[130:131], off
	s_nop 0
	global_load_dwordx4 v[134:137], v[134:135], off
	v_addc_co_u32_e32 v139, vcc, 0, v177, vcc
	global_load_dwordx4 v[138:141], v[138:139], off offset:2048
